# hyena jobs (P2 critical path) run at s_setprio 3 against the co-resident general-queue block
# speedup vs baseline: 1.0391x; 1.0148x over previous
; #define LAUNDER(v) asm volatile("" : "+s"(v))
; __device__ __forceinline__ int vtid() { int t = threadIdx.x; asm volatile("" : "+v"(t)); return t; }
; __device__ __forceinline__ void hyena_lat_job(const Params& p, char* smem, int l, int c) {
;   const int tid = vtid(), lane = tid & 63, w = __builtin_amdgcn_readfirstlane(tid >> 6), r = lane & 31, h = lane >> 5;
;   char* ws = p.ws;
;   LAUNDER(ws); LAUNDER(l);
;   u16* zs = (u16*)smem;
;   u16* Es = (u16*)(smem + 40960);
;   u16* Fs = (u16*)(smem + 40960 + 18688);
;   const u16* UT = (const u16*)(ws + OFF_UT);
;   u16* MIX = (u16*)(ws + OFF_MIX);
;   const float* cw = p.hy_conv_w + l * 3 * 768;
;   const float* cb = p.hy_conv_b + l * 768;
;   __syncthreads();
;   {
;     int gc = 512 + c;
;     float w0 = cw[gc], w1 = cw[768 + gc], w2 = cw[1536 + gc], bb = cb[gc];
;     const u16* u = UT + (size_t)gc * MTOT;
;     if (tid < 4) *(unsigned*)&zs[32 + tid * 2] = 0u;
;     for (int i4 = tid; i4 < 4096; i4 += 256) {
.LBB0_972:
	s_setprio 3
	v_readlane_b32 s4, v239, 63
	v_mov_b32_e32 v0, v172
	s_mov_b64 s[0:1], s[58:59]
	s_mov_b32 s2, s4
	v_readlane_b32 s5, v238, 0
	s_mul_i32 s4, s2, 0x900
	s_ashr_i32 s5, s4, 31
	s_lshl_b64 s[4:5], s[4:5], 2
	s_add_u32 s20, s86, s4
	s_mul_i32 s4, s2, 0x300
	s_addc_u32 s21, s87, s5
	s_ashr_i32 s5, s4, 31
	s_lshl_b64 s[4:5], s[4:5], 2
	s_add_u32 s22, s88, s4
	s_mov_b32 s11, s3
	s_addc_u32 s23, s89, s5
	s_lshl_b64 s[4:5], s[10:11], 2
	s_add_u32 s12, s20, s4
	s_addc_u32 s13, s21, s5
	s_add_u32 s4, s22, s4
	s_barrier
	global_load_dword v2, v1, s[12:13] offset:2048
	global_load_dword v4, v200, s[12:13] offset:1024
	global_load_dword v6, v199, s[12:13]
	s_addc_u32 s5, s23, s5
	global_load_dword v8, v1, s[4:5] offset:2048
	v_readfirstlane_b32 s24, v0
	v_cmp_gt_i32_e32 vcc, 4, v0
	v_lshlrev_b32_e32 v10, 2, v0
	s_and_saveexec_b64 s[4:5], vcc
	v_lshlrev_b32_e32 v3, 2, v0
	ds_write_b32 v3, v1 offset:64
	s_or_b64 exec, exec, s[4:5]
	s_add_u32 s4, s0, 0x267d6100
	s_movk_i32 s12, 0x1000
	s_addc_u32 s5, s1, 0
	v_cmp_gt_i32_e32 vcc, s12, v0
	s_and_saveexec_b64 s[12:13], vcc
	s_cbranch_execz .LBB0_981
	s_or_b32 s14, s10, 0x200
	s_mul_hi_u32 s15, s14, 0x8400
	s_mul_i32 s14, s14, 0x8400
	s_add_u32 s14, s4, s14
	s_addc_u32 s15, s5, s15
	s_waitcnt vmcnt(0)
	v_mov_b32_e32 v3, v2
	v_mov_b32_e32 v9, v8
	v_mov_b32_e32 v5, v4
	v_mov_b32_e32 v7, v6
	s_mov_b64 s[16:17], 0
	v_mov_b32_e32 v18, v0
	s_branch .LBB0_977

; __device__ __forceinline__ void hyena_lat_job(const Params& p, char* smem, int l, int c) {
;     ...
;   __syncthreads();
.LBB0_1145:
	s_setprio 0
	s_waitcnt lgkmcnt(0)
	s_barrier
	s_cbranch_execnz .LBB0_714
